# EpiScale epilogue: rstd-table LDS reads batched, norm-weight loads issued before the sum-of-squares round trip, transposed stores delayed one section so LDS write/read latency overlaps
# baseline (speedup 1.0000x reference)
; #define PG8_LAS __attribute__((address_space(3)))
; __device__ __forceinline__ float row_rstd(const float* ss, int row) {
;     const f32x4 a = *(const f32x4*)(ss + (size_t)row * 8), b = *(const f32x4*)(ss + (size_t)row * 8 + 4);
;     const float s = ((a[0] + a[1]) + (a[2] + a[3])) + ((b[0] + b[1]) + (b[2] + b[3]));
;     return 1.0f / sqrtf(s * (1.0f / 2048.0f) + 1e-6f);
; }
;     __device__ __forceinline__ void operator()(const f32x4 (&acc)[2][2][4][2], const Unit& u, int wr, int wc, int fr, int fq, PG8_LAS unsigned char* lds, int wid, int lane) const {
;         const int colt = u.pn * BM; const int col0 = colt + wc * 32 + 8 * fq;
;         PG8_LAS float* tbl = (PG8_LAS float*)(lds + 131072 + 10240);
;         PG8_LAS unsigned char* st = lds + 131072 + wid * 1280;
;         { const int t = wid * 64 + lane; if (t < 256) tbl[t] = row_rstd(ss, u.pm * BM + t); }
;         f32x4 bv[2][2];
; #pragma unroll
;         for (int bj = 0; bj < 2; ++bj)
; #pragma unroll
;             for (int n = 0; n < 2; ++n) bv[bj][n] = bias ? *(const f32x4*)(bias + col0 + bj * HALF + 4 * n) : (f32x4){0.f, 0.f, 0.f, 0.f};
.LBB0_504:
	s_lshl_b32 s0, s79, 8
	v_or_b32_e32 v136, s0, v165
	v_readlane_b32 s4, v252, 47
	v_ashrrev_i32_e32 v137, 31, v136
	v_readlane_b32 s5, v252, 48
	s_andn2_b64 vcc, exec, s[10:11]
	v_mov_b32_e32 v144, 0
	v_lshl_add_u64 v[162:163], v[136:137], 2, s[4:5]
	v_cndmask_b32_e64 v137, 0, 1, s[10:11]
	v_mov_b32_e32 v136, 0
	v_cmp_ne_u32_e64 s[4:5], 1, v137
	v_mov_b32_e32 v145, 0
	v_mov_b32_e32 v146, 0
	v_mov_b32_e32 v147, 0
	s_cbranch_vccnz .LBB0_508
	global_load_dwordx4 v[144:147], v[162:163], off

; __device__ __forceinline__ float row_rstd(const float* ss, int row) {
;     const f32x4 a = *(const f32x4*)(ss + (size_t)row * 8), b = *(const f32x4*)(ss + (size_t)row * 8 + 4);
;     const float s = ((a[0] + a[1]) + (a[2] + a[3])) + ((b[0] + b[1]) + (b[2] + b[3]));
;     return 1.0f / sqrtf(s * (1.0f / 2048.0f) + 1e-6f);
;     __device__ __forceinline__ void operator()(const f32x4 (&acc)[2][2][4][2], const Unit& u, int wr, int wc, int fr, int fq, PG8_LAS unsigned char* lds, int wid, int lane) const {
;     ...
;         { const int t = wid * 64 + lane; if (t < 256) tbl[t] = row_rstd(ss, u.pm * BM + t); }
.Lmy_ss:
	s_and_saveexec_b64 s[4:5], s[38:39]
	s_cbranch_execz .LBB0_506
	v_lshl_add_u32 v198, s37, 8, v166
	v_ashrrev_i32_e32 v199, 31, v198
	v_lshlrev_b64 v[198:199], 5, v[198:199]
	v_lshl_add_u64 v[202:203], s[28:29], 0, v[198:199]
	global_load_dwordx4 v[198:201], v[202:203], off
	s_nop 0
	global_load_dwordx4 v[202:205], v[202:203], off offset:16
	s_mov_b32 s98, 0xf800000
	s_waitcnt vmcnt(0)
	v_mov_b32_e32 v206, v198
	v_mov_b32_e32 v207, v202
	v_mov_b32_e32 v202, v199
	v_mov_b32_e32 v198, v200
	v_mov_b32_e32 v199, v204
	v_mov_b32_e32 v204, v201
	v_pk_add_f32 v[200:201], v[206:207], v[202:203]
	v_pk_add_f32 v[198:199], v[198:199], v[204:205]
	s_nop 0
	v_pk_add_f32 v[198:199], v[200:201], v[198:199]
	s_nop 0
	v_add_f32_e32 v198, v198, v199
	v_fmamk_f32 v198, v198, 0x3a000000, v210
	v_mul_f32_e32 v199, 0x4f800000, v198
	v_cmp_gt_f32_e32 vcc, s98, v198
	s_nop 1
	v_cndmask_b32_e32 v198, v198, v199, vcc
	v_sqrt_f32_e32 v199, v198
	s_nop 0
	v_add_u32_e32 v200, -1, v199
	v_add_u32_e32 v201, 1, v199
	v_fma_f32 v202, -v200, v199, v198
	v_fma_f32 v203, -v201, v199, v198
	v_cmp_ge_f32_e64 s[98:99], 0, v202
	s_nop 1
	v_cndmask_b32_e64 v199, v199, v200, s[98:99]
	v_cmp_lt_f32_e64 s[98:99], 0, v203
	s_nop 1
	v_cndmask_b32_e64 v199, v199, v201, s[98:99]
	v_mul_f32_e32 v200, 0x37800000, v199
	v_cndmask_b32_e32 v199, v199, v200, vcc
	v_cmp_class_f32_e32 vcc, v198, v211
	s_nop 1
	v_cndmask_b32_e32 v198, v199, v198, vcc
	v_div_scale_f32 v199, s[98:99], v198, v198, 1.0
	v_rcp_f32_e32 v200, v199
	v_div_scale_f32 v201, vcc, 1.0, v198, 1.0
	v_fma_f32 v202, -v199, v200, 1.0
	v_fmac_f32_e32 v200, v202, v200
	v_mul_f32_e32 v202, v201, v200
	v_fma_f32 v203, -v199, v202, v201
	v_fmac_f32_e32 v202, v203, v200
	v_fma_f32 v199, -v199, v202, v201
	v_div_fmas_f32 v199, v199, v200, v202
	v_div_fixup_f32 v198, v199, v198, 1.0
	ds_write_b32 v167, v198

; #define PG8_LAS __attribute__((address_space(3)))
; __device__ __forceinline__ unsigned cvt_pk_bf16(float lo, float hi) { unsigned r; asm volatile("v_cvt_pk_bf16_f32 %0, %1, %2" : "=v"(r) : "v"(lo), "v"(hi)); return r; }
;     __device__ __forceinline__ void operator()(const f32x4 (&acc)[2][2][4][2], const Unit& u, int wr, int wc, int fr, int fq, PG8_LAS unsigned char* lds, int wid, int lane) const {
;     ...
;         const float cs = (mode == 2 && colt < 2048) ? 0.125f : 1.0f;
;         asm volatile("s_waitcnt lgkmcnt(0)" ::: "memory"); __builtin_amdgcn_s_barrier(); asm volatile("" ::: "memory");
;         bf16_t* obase = O + (size_t)(u.pm * BM + wr * 64 + (lane >> 2)) * ldc + colt + wc * 32 + 8 * (lane & 3);
; #pragma unroll
;         for (int ai = 0; ai < 2; ++ai)
; #pragma unroll
;             for (int m = 0; m < 4; ++m) { const float rs = tbl[ai * HALF + wr * 64 + m * 16 + fr];
; #pragma unroll
;                 for (int bj = 0; bj < 2; ++bj) { const f32x4 v0 = (acc[ai][bj][m][0] * rs + bv[bj][0]) * cs, v1 = (acc[ai][bj][m][1] * rs + bv[bj][1]) * cs;
;                     u32x4 w; w.x = cvt_pk_bf16(v0[0], v0[1]); w.y = cvt_pk_bf16(v0[2], v0[3]); w.z = cvt_pk_bf16(v1[0], v1[1]); w.w = cvt_pk_bf16(v1[2], v1[3]);
;                     *(PG8_LAS u32x4*)(st + fr * 80 + fq * 16) = w;
;                     const u32x4 x = *(const PG8_LAS u32x4*)(st + (lane >> 2) * 80 + (lane & 3) * 16);
;                     *(u32x4*)(obase + (size_t)(ai * HALF + m * 16) * ldc + bj * HALF) = x; } }
.LBB0_514:
	s_cmp_lt_i32 s79, 8
	v_readlane_b32 s42, v252, 38
	v_lshl_add_u32 v163, s37, 8, v168
	s_cselect_b64 s[4:5], -1, 0
	v_readlane_b32 s43, v252, 39
	v_ashrrev_i32_e32 v173, 31, v163
	s_and_b64 vcc, s[42:43], s[4:5]
	s_waitcnt lgkmcnt(0)
	s_barrier
	v_mul_lo_u32 v173, s26, v173
	v_mul_lo_u32 v176, s27, v163
	v_mad_u64_u32 v[174:175], s[4:5], s26, v163, 0
	v_add3_u32 v175, v175, v173, v176
	ds_read_b32 v176, v169
	ds_read_b32 v184, v169 offset:64
	ds_read_b32 v186, v169 offset:128
	ds_read_b32 v188, v169 offset:192
	ds_read_b32 v190, v169 offset:512
	ds_read_b32 v192, v169 offset:576
	ds_read_b32 v194, v169 offset:640
	ds_read_b32 v196, v169 offset:704
	v_mov_b32_e32 v162, 0x3e000000
	v_cndmask_b32_e32 v162, 1.0, v162, vcc
	v_readlane_b32 s4, v252, 45
	v_readlane_b32 s5, v252, 46
	s_waitcnt vmcnt(0) lgkmcnt(0)
	v_pk_fma_f32 v[128:129], v[128:129], v[176:177], v[136:137] op_sel_hi:[1,0,1]
	v_pk_fma_f32 v[130:131], v[130:131], v[176:177], v[138:139] op_sel_hi:[1,0,1]
	v_pk_fma_f32 v[132:133], v[132:133], v[176:177], v[144:145] op_sel_hi:[1,0,1]
	v_pk_fma_f32 v[134:135], v[134:135], v[176:177], v[146:147] op_sel_hi:[1,0,1]
	v_pk_mul_f32 v[178:179], v[162:163], v[130:131] op_sel_hi:[0,1]
	v_pk_mul_f32 v[130:131], v[162:163], v[128:129] op_sel_hi:[0,1]
	v_pk_mul_f32 v[134:135], v[162:163], v[134:135] op_sel_hi:[0,1]
	v_pk_mul_f32 v[132:133], v[162:163], v[132:133] op_sel_hi:[0,1]
	v_cvt_pk_bf16_f32 v128, v132, v133
	v_cvt_pk_bf16_f32 v129, v134, v135
	v_cvt_pk_bf16_f32 v130, v130, v131
	v_cvt_pk_bf16_f32 v131, v178, v179
	ds_write_b128 v171, v[128:131]
	ds_read_b128 v[128:131], v172
	v_lshl_add_u64 v[174:175], v[174:175], 1, s[4:5]
	s_ashr_i32 s1, s0, 31
	v_lshl_add_u64 v[174:175], s[0:1], 1, v[174:175]
	v_lshl_add_u64 v[174:175], v[174:175], 0, s[20:21]
	v_lshl_add_u64 v[174:175], v[174:175], 0, v[0:1]
	v_pk_fma_f32 v[120:121], v[120:121], v[176:177], v[140:141] op_sel_hi:[1,0,1]
	v_pk_fma_f32 v[122:123], v[122:123], v[176:177], v[142:143] op_sel_hi:[1,0,1]
	v_pk_fma_f32 v[124:125], v[124:125], v[176:177], v[148:149] op_sel_hi:[1,0,1]
	v_pk_fma_f32 v[126:127], v[126:127], v[176:177], v[150:151] op_sel_hi:[1,0,1]
	v_pk_mul_f32 v[198:199], v[162:163], v[122:123] op_sel_hi:[0,1]
	v_pk_mul_f32 v[122:123], v[162:163], v[120:121] op_sel_hi:[0,1]
	v_pk_mul_f32 v[126:127], v[162:163], v[126:127] op_sel_hi:[0,1]
	v_pk_mul_f32 v[124:125], v[162:163], v[124:125] op_sel_hi:[0,1]
	v_cvt_pk_bf16_f32 v120, v124, v125
	v_cvt_pk_bf16_f32 v121, v126, v127
	v_cvt_pk_bf16_f32 v122, v122, v123
	v_cvt_pk_bf16_f32 v123, v198, v199
	ds_write_b128 v171, v[120:123]
	ds_read_b128 v[120:123], v172
	s_waitcnt lgkmcnt(2)
	global_store_dwordx4 v[174:175], v[128:131], off nt
	s_mov_b64 s[0:1], -1
	s_and_b64 vcc, exec, s[2:3]
	v_pk_fma_f32 v[112:113], v[112:113], v[184:185], v[136:137] op_sel_hi:[1,0,1]
	v_pk_fma_f32 v[114:115], v[114:115], v[184:185], v[138:139] op_sel_hi:[1,0,1]
	v_pk_fma_f32 v[116:117], v[116:117], v[184:185], v[144:145] op_sel_hi:[1,0,1]
	v_pk_fma_f32 v[118:119], v[118:119], v[184:185], v[146:147] op_sel_hi:[1,0,1]
	v_pk_mul_f32 v[200:201], v[162:163], v[114:115] op_sel_hi:[0,1]
	v_pk_mul_f32 v[114:115], v[162:163], v[112:113] op_sel_hi:[0,1]
	v_pk_mul_f32 v[118:119], v[162:163], v[118:119] op_sel_hi:[0,1]
	v_pk_mul_f32 v[116:117], v[162:163], v[116:117] op_sel_hi:[0,1]
	v_cvt_pk_bf16_f32 v112, v116, v117
	v_cvt_pk_bf16_f32 v113, v118, v119
	v_cvt_pk_bf16_f32 v114, v114, v115
	v_cvt_pk_bf16_f32 v115, v200, v201
	ds_write_b128 v171, v[112:115]
	ds_read_b128 v[112:115], v172
	s_waitcnt lgkmcnt(2)
	global_store_dwordx4 v[174:175], v[120:123], off offset:256 nt
	v_lshl_add_u64 v[116:117], v[174:175], 0, s[54:55]
	v_pk_fma_f32 v[104:105], v[104:105], v[184:185], v[140:141] op_sel_hi:[1,0,1]
	v_pk_fma_f32 v[106:107], v[106:107], v[184:185], v[142:143] op_sel_hi:[1,0,1]
	v_pk_fma_f32 v[108:109], v[108:109], v[184:185], v[148:149] op_sel_hi:[1,0,1]
	v_pk_fma_f32 v[110:111], v[110:111], v[184:185], v[150:151] op_sel_hi:[1,0,1]
	v_pk_mul_f32 v[108:109], v[162:163], v[108:109] op_sel_hi:[0,1]
	v_pk_mul_f32 v[202:203], v[162:163], v[106:107] op_sel_hi:[0,1]
	v_pk_mul_f32 v[106:107], v[162:163], v[104:105] op_sel_hi:[0,1]
	v_pk_mul_f32 v[110:111], v[162:163], v[110:111] op_sel_hi:[0,1]
	v_cvt_pk_bf16_f32 v104, v108, v109
	v_cvt_pk_bf16_f32 v105, v110, v111
	v_cvt_pk_bf16_f32 v106, v106, v107
	v_cvt_pk_bf16_f32 v107, v202, v203
	ds_write_b128 v171, v[104:107]
	ds_read_b128 v[104:107], v172
	s_waitcnt lgkmcnt(2)
	global_store_dwordx4 v[116:117], v[112:115], off nt
	v_pk_fma_f32 v[96:97], v[96:97], v[186:187], v[136:137] op_sel_hi:[1,0,1]
	v_pk_fma_f32 v[98:99], v[98:99], v[186:187], v[138:139] op_sel_hi:[1,0,1]
	v_pk_fma_f32 v[100:101], v[100:101], v[186:187], v[144:145] op_sel_hi:[1,0,1]
	v_pk_fma_f32 v[102:103], v[102:103], v[186:187], v[146:147] op_sel_hi:[1,0,1]
	v_pk_mul_f32 v[204:205], v[162:163], v[98:99] op_sel_hi:[0,1]
	v_pk_mul_f32 v[98:99], v[162:163], v[96:97] op_sel_hi:[0,1]
	v_pk_mul_f32 v[102:103], v[162:163], v[102:103] op_sel_hi:[0,1]
	v_pk_mul_f32 v[100:101], v[162:163], v[100:101] op_sel_hi:[0,1]
	v_cvt_pk_bf16_f32 v96, v100, v101
	v_cvt_pk_bf16_f32 v97, v102, v103
	v_cvt_pk_bf16_f32 v98, v98, v99
	v_cvt_pk_bf16_f32 v99, v204, v205
	ds_write_b128 v171, v[96:99]
	ds_read_b128 v[96:99], v172
	s_waitcnt lgkmcnt(2)
; #define PG8_LAS __attribute__((address_space(3)))
; __device__ __forceinline__ unsigned cvt_pk_bf16(float lo, float hi) { unsigned r; asm volatile("v_cvt_pk_bf16_f32 %0, %1, %2" : "=v"(r) : "v"(lo), "v"(hi)); return r; }
;     __device__ __forceinline__ void operator()(const f32x4 (&acc)[2][2][4][2], const Unit& u, int wr, int wc, int fr, int fq, PG8_LAS unsigned char* lds, int wid, int lane) const {
;     ...
;             for (int m = 0; m < 4; ++m) { const float rs = tbl[ai * HALF + wr * 64 + m * 16 + fr];
; #pragma unroll
;                 for (int bj = 0; bj < 2; ++bj) { const f32x4 v0 = (acc[ai][bj][m][0] * rs + bv[bj][0]) * cs, v1 = (acc[ai][bj][m][1] * rs + bv[bj][1]) * cs;
;                     u32x4 w; w.x = cvt_pk_bf16(v0[0], v0[1]); w.y = cvt_pk_bf16(v0[2], v0[3]); w.z = cvt_pk_bf16(v1[0], v1[1]); w.w = cvt_pk_bf16(v1[2], v1[3]);
;                     *(PG8_LAS u32x4*)(st + fr * 80 + fq * 16) = w;
;                     const u32x4 x = *(const PG8_LAS u32x4*)(st + (lane >> 2) * 80 + (lane & 3) * 16);
;                     *(u32x4*)(obase + (size_t)(ai * HALF + m * 16) * ldc + bj * HALF) = x; } }
	global_store_dwordx4 v[116:117], v[104:107], off offset:256 nt
	v_lshl_add_u64 v[100:101], v[116:117], 0, s[54:55]
	v_pk_fma_f32 v[88:89], v[88:89], v[186:187], v[140:141] op_sel_hi:[1,0,1]
	v_pk_fma_f32 v[90:91], v[90:91], v[186:187], v[142:143] op_sel_hi:[1,0,1]
	v_pk_fma_f32 v[92:93], v[92:93], v[186:187], v[148:149] op_sel_hi:[1,0,1]
	v_pk_fma_f32 v[94:95], v[94:95], v[186:187], v[150:151] op_sel_hi:[1,0,1]
	v_pk_mul_f32 v[92:93], v[162:163], v[92:93] op_sel_hi:[0,1]
	v_pk_mul_f32 v[198:199], v[162:163], v[90:91] op_sel_hi:[0,1]
	v_pk_mul_f32 v[90:91], v[162:163], v[88:89] op_sel_hi:[0,1]
	v_pk_mul_f32 v[94:95], v[162:163], v[94:95] op_sel_hi:[0,1]
	v_cvt_pk_bf16_f32 v88, v92, v93
	v_cvt_pk_bf16_f32 v89, v94, v95
	v_cvt_pk_bf16_f32 v90, v90, v91
	v_cvt_pk_bf16_f32 v91, v198, v199
	ds_write_b128 v171, v[88:91]
	ds_read_b128 v[88:91], v172
	s_waitcnt lgkmcnt(2)
	global_store_dwordx4 v[100:101], v[96:99], off nt
	v_pk_fma_f32 v[80:81], v[80:81], v[188:189], v[136:137] op_sel_hi:[1,0,1]
	v_pk_fma_f32 v[82:83], v[82:83], v[188:189], v[138:139] op_sel_hi:[1,0,1]
	v_pk_fma_f32 v[84:85], v[84:85], v[188:189], v[144:145] op_sel_hi:[1,0,1]
	v_pk_fma_f32 v[86:87], v[86:87], v[188:189], v[146:147] op_sel_hi:[1,0,1]
	v_pk_mul_f32 v[200:201], v[162:163], v[82:83] op_sel_hi:[0,1]
	v_pk_mul_f32 v[82:83], v[162:163], v[80:81] op_sel_hi:[0,1]
	v_pk_mul_f32 v[86:87], v[162:163], v[86:87] op_sel_hi:[0,1]
	v_pk_mul_f32 v[84:85], v[162:163], v[84:85] op_sel_hi:[0,1]
	v_cvt_pk_bf16_f32 v80, v84, v85
	v_cvt_pk_bf16_f32 v81, v86, v87
	v_cvt_pk_bf16_f32 v82, v82, v83
	v_cvt_pk_bf16_f32 v83, v200, v201
	ds_write_b128 v171, v[80:83]
	ds_read_b128 v[80:83], v172
	s_waitcnt lgkmcnt(2)
	global_store_dwordx4 v[100:101], v[88:91], off offset:256 nt
	v_lshl_add_u64 v[84:85], v[100:101], 0, s[54:55]
	v_pk_fma_f32 v[72:73], v[72:73], v[188:189], v[140:141] op_sel_hi:[1,0,1]
	v_pk_fma_f32 v[74:75], v[74:75], v[188:189], v[142:143] op_sel_hi:[1,0,1]
	v_pk_fma_f32 v[76:77], v[76:77], v[188:189], v[148:149] op_sel_hi:[1,0,1]
	v_pk_fma_f32 v[78:79], v[78:79], v[188:189], v[150:151] op_sel_hi:[1,0,1]
	v_pk_mul_f32 v[76:77], v[162:163], v[76:77] op_sel_hi:[0,1]
	v_pk_mul_f32 v[202:203], v[162:163], v[74:75] op_sel_hi:[0,1]
	v_pk_mul_f32 v[74:75], v[162:163], v[72:73] op_sel_hi:[0,1]
	v_pk_mul_f32 v[78:79], v[162:163], v[78:79] op_sel_hi:[0,1]
	v_cvt_pk_bf16_f32 v72, v76, v77
	v_cvt_pk_bf16_f32 v73, v78, v79
	v_cvt_pk_bf16_f32 v74, v74, v75
	v_cvt_pk_bf16_f32 v75, v202, v203
	ds_write_b128 v171, v[72:75]
	ds_read_b128 v[72:75], v172
	s_waitcnt lgkmcnt(2)
	global_store_dwordx4 v[84:85], v[80:83], off nt
	v_pk_fma_f32 v[64:65], v[64:65], v[190:191], v[136:137] op_sel_hi:[1,0,1]
	v_pk_fma_f32 v[66:67], v[66:67], v[190:191], v[138:139] op_sel_hi:[1,0,1]
	v_pk_fma_f32 v[68:69], v[68:69], v[190:191], v[144:145] op_sel_hi:[1,0,1]
	v_pk_fma_f32 v[70:71], v[70:71], v[190:191], v[146:147] op_sel_hi:[1,0,1]
	v_pk_mul_f32 v[204:205], v[162:163], v[66:67] op_sel_hi:[0,1]
	v_pk_mul_f32 v[66:67], v[162:163], v[64:65] op_sel_hi:[0,1]
	v_pk_mul_f32 v[70:71], v[162:163], v[70:71] op_sel_hi:[0,1]
	v_pk_mul_f32 v[68:69], v[162:163], v[68:69] op_sel_hi:[0,1]
	v_cvt_pk_bf16_f32 v64, v68, v69
	v_cvt_pk_bf16_f32 v65, v70, v71
	v_cvt_pk_bf16_f32 v66, v66, v67
	v_cvt_pk_bf16_f32 v67, v204, v205
	ds_write_b128 v171, v[64:67]
	ds_read_b128 v[64:67], v172
	s_waitcnt lgkmcnt(2)
	global_store_dwordx4 v[84:85], v[72:75], off offset:256 nt
	v_lshl_add_u64 v[68:69], v[84:85], 0, s[16:17]
	v_pk_fma_f32 v[56:57], v[56:57], v[190:191], v[140:141] op_sel_hi:[1,0,1]
	v_pk_fma_f32 v[58:59], v[58:59], v[190:191], v[142:143] op_sel_hi:[1,0,1]
	v_pk_fma_f32 v[60:61], v[60:61], v[190:191], v[148:149] op_sel_hi:[1,0,1]
	v_pk_fma_f32 v[62:63], v[62:63], v[190:191], v[150:151] op_sel_hi:[1,0,1]
	v_pk_mul_f32 v[60:61], v[162:163], v[60:61] op_sel_hi:[0,1]
	v_pk_mul_f32 v[198:199], v[162:163], v[58:59] op_sel_hi:[0,1]
	v_pk_mul_f32 v[58:59], v[162:163], v[56:57] op_sel_hi:[0,1]
	v_pk_mul_f32 v[62:63], v[162:163], v[62:63] op_sel_hi:[0,1]
	v_cvt_pk_bf16_f32 v56, v60, v61
	v_cvt_pk_bf16_f32 v57, v62, v63
	v_cvt_pk_bf16_f32 v58, v58, v59
	v_cvt_pk_bf16_f32 v59, v198, v199
	ds_write_b128 v171, v[56:59]
	ds_read_b128 v[56:59], v172
	s_waitcnt lgkmcnt(2)
	global_store_dwordx4 v[68:69], v[64:67], off nt
	v_pk_fma_f32 v[48:49], v[48:49], v[192:193], v[136:137] op_sel_hi:[1,0,1]
	v_pk_fma_f32 v[50:51], v[50:51], v[192:193], v[138:139] op_sel_hi:[1,0,1]
	v_pk_fma_f32 v[52:53], v[52:53], v[192:193], v[144:145] op_sel_hi:[1,0,1]
	v_pk_fma_f32 v[54:55], v[54:55], v[192:193], v[146:147] op_sel_hi:[1,0,1]
	v_pk_mul_f32 v[200:201], v[162:163], v[50:51] op_sel_hi:[0,1]
	v_pk_mul_f32 v[50:51], v[162:163], v[48:49] op_sel_hi:[0,1]
	v_pk_mul_f32 v[54:55], v[162:163], v[54:55] op_sel_hi:[0,1]
	v_pk_mul_f32 v[52:53], v[162:163], v[52:53] op_sel_hi:[0,1]
	v_cvt_pk_bf16_f32 v48, v52, v53
	v_cvt_pk_bf16_f32 v49, v54, v55
	v_cvt_pk_bf16_f32 v50, v50, v51
	v_cvt_pk_bf16_f32 v51, v200, v201
	ds_write_b128 v171, v[48:51]
	ds_read_b128 v[48:51], v172
	s_waitcnt lgkmcnt(2)
; #define PG8_LAS __attribute__((address_space(3)))
; __device__ __forceinline__ unsigned cvt_pk_bf16(float lo, float hi) { unsigned r; asm volatile("v_cvt_pk_bf16_f32 %0, %1, %2" : "=v"(r) : "v"(lo), "v"(hi)); return r; }
;     __device__ __forceinline__ void operator()(const f32x4 (&acc)[2][2][4][2], const Unit& u, int wr, int wc, int fr, int fq, PG8_LAS unsigned char* lds, int wid, int lane) const {
;     ...
;             for (int m = 0; m < 4; ++m) { const float rs = tbl[ai * HALF + wr * 64 + m * 16 + fr];
; #pragma unroll
;                 for (int bj = 0; bj < 2; ++bj) { const f32x4 v0 = (acc[ai][bj][m][0] * rs + bv[bj][0]) * cs, v1 = (acc[ai][bj][m][1] * rs + bv[bj][1]) * cs;
;                     u32x4 w; w.x = cvt_pk_bf16(v0[0], v0[1]); w.y = cvt_pk_bf16(v0[2], v0[3]); w.z = cvt_pk_bf16(v1[0], v1[1]); w.w = cvt_pk_bf16(v1[2], v1[3]);
;                     *(PG8_LAS u32x4*)(st + fr * 80 + fq * 16) = w;
;                     const u32x4 x = *(const PG8_LAS u32x4*)(st + (lane >> 2) * 80 + (lane & 3) * 16);
;                     *(u32x4*)(obase + (size_t)(ai * HALF + m * 16) * ldc + bj * HALF) = x; } }
	global_store_dwordx4 v[68:69], v[56:59], off offset:256 nt
	v_lshl_add_u64 v[52:53], v[68:69], 0, s[54:55]
	v_pk_fma_f32 v[40:41], v[40:41], v[192:193], v[140:141] op_sel_hi:[1,0,1]
	v_pk_fma_f32 v[42:43], v[42:43], v[192:193], v[142:143] op_sel_hi:[1,0,1]
	v_pk_fma_f32 v[44:45], v[44:45], v[192:193], v[148:149] op_sel_hi:[1,0,1]
	v_pk_fma_f32 v[46:47], v[46:47], v[192:193], v[150:151] op_sel_hi:[1,0,1]
	v_pk_mul_f32 v[44:45], v[162:163], v[44:45] op_sel_hi:[0,1]
	v_pk_mul_f32 v[202:203], v[162:163], v[42:43] op_sel_hi:[0,1]
	v_pk_mul_f32 v[42:43], v[162:163], v[40:41] op_sel_hi:[0,1]
	v_pk_mul_f32 v[46:47], v[162:163], v[46:47] op_sel_hi:[0,1]
	v_cvt_pk_bf16_f32 v40, v44, v45
	v_cvt_pk_bf16_f32 v41, v46, v47
	v_cvt_pk_bf16_f32 v42, v42, v43
	v_cvt_pk_bf16_f32 v43, v202, v203
	ds_write_b128 v171, v[40:43]
	ds_read_b128 v[40:43], v172
	s_waitcnt lgkmcnt(2)
	global_store_dwordx4 v[52:53], v[48:51], off nt
	v_pk_fma_f32 v[32:33], v[32:33], v[194:195], v[136:137] op_sel_hi:[1,0,1]
	v_pk_fma_f32 v[34:35], v[34:35], v[194:195], v[138:139] op_sel_hi:[1,0,1]
	v_pk_fma_f32 v[36:37], v[36:37], v[194:195], v[144:145] op_sel_hi:[1,0,1]
	v_pk_fma_f32 v[38:39], v[38:39], v[194:195], v[146:147] op_sel_hi:[1,0,1]
	v_pk_mul_f32 v[204:205], v[162:163], v[34:35] op_sel_hi:[0,1]
	v_pk_mul_f32 v[34:35], v[162:163], v[32:33] op_sel_hi:[0,1]
	v_pk_mul_f32 v[38:39], v[162:163], v[38:39] op_sel_hi:[0,1]
	v_pk_mul_f32 v[36:37], v[162:163], v[36:37] op_sel_hi:[0,1]
	v_cvt_pk_bf16_f32 v32, v36, v37
	v_cvt_pk_bf16_f32 v33, v38, v39
	v_cvt_pk_bf16_f32 v34, v34, v35
	v_cvt_pk_bf16_f32 v35, v204, v205
	ds_write_b128 v171, v[32:35]
	ds_read_b128 v[32:35], v172
	s_waitcnt lgkmcnt(2)
	global_store_dwordx4 v[52:53], v[40:43], off offset:256 nt
	v_lshl_add_u64 v[36:37], v[52:53], 0, s[54:55]
	v_pk_fma_f32 v[24:25], v[24:25], v[194:195], v[140:141] op_sel_hi:[1,0,1]
	v_pk_fma_f32 v[26:27], v[26:27], v[194:195], v[142:143] op_sel_hi:[1,0,1]
	v_pk_fma_f32 v[28:29], v[28:29], v[194:195], v[148:149] op_sel_hi:[1,0,1]
	v_pk_fma_f32 v[30:31], v[30:31], v[194:195], v[150:151] op_sel_hi:[1,0,1]
	v_pk_mul_f32 v[28:29], v[162:163], v[28:29] op_sel_hi:[0,1]
	v_pk_mul_f32 v[198:199], v[162:163], v[26:27] op_sel_hi:[0,1]
	v_pk_mul_f32 v[26:27], v[162:163], v[24:25] op_sel_hi:[0,1]
	v_pk_mul_f32 v[30:31], v[162:163], v[30:31] op_sel_hi:[0,1]
	v_cvt_pk_bf16_f32 v24, v28, v29
	v_cvt_pk_bf16_f32 v25, v30, v31
	v_cvt_pk_bf16_f32 v26, v26, v27
	v_cvt_pk_bf16_f32 v27, v198, v199
	ds_write_b128 v171, v[24:27]
	ds_read_b128 v[24:27], v172
	s_waitcnt lgkmcnt(2)
	global_store_dwordx4 v[36:37], v[32:35], off nt
	v_pk_fma_f32 v[16:17], v[16:17], v[196:197], v[136:137] op_sel_hi:[1,0,1]
	v_pk_fma_f32 v[18:19], v[18:19], v[196:197], v[138:139] op_sel_hi:[1,0,1]
	v_pk_fma_f32 v[20:21], v[20:21], v[196:197], v[144:145] op_sel_hi:[1,0,1]
	v_pk_fma_f32 v[22:23], v[22:23], v[196:197], v[146:147] op_sel_hi:[1,0,1]
	v_pk_mul_f32 v[200:201], v[162:163], v[18:19] op_sel_hi:[0,1]
	v_pk_mul_f32 v[18:19], v[162:163], v[16:17] op_sel_hi:[0,1]
	v_pk_mul_f32 v[22:23], v[162:163], v[22:23] op_sel_hi:[0,1]
	v_pk_mul_f32 v[20:21], v[162:163], v[20:21] op_sel_hi:[0,1]
	v_cvt_pk_bf16_f32 v16, v20, v21
	v_cvt_pk_bf16_f32 v17, v22, v23
	v_cvt_pk_bf16_f32 v18, v18, v19
	v_cvt_pk_bf16_f32 v19, v200, v201
	ds_write_b128 v171, v[16:19]
	ds_read_b128 v[16:19], v172
	s_waitcnt lgkmcnt(2)
	global_store_dwordx4 v[36:37], v[24:27], off offset:256 nt
	v_lshl_add_u64 v[20:21], v[36:37], 0, s[54:55]
	v_pk_fma_f32 v[8:9], v[8:9], v[196:197], v[140:141] op_sel_hi:[1,0,1]
	v_pk_fma_f32 v[10:11], v[10:11], v[196:197], v[142:143] op_sel_hi:[1,0,1]
	v_pk_fma_f32 v[12:13], v[12:13], v[196:197], v[148:149] op_sel_hi:[1,0,1]
	v_pk_fma_f32 v[14:15], v[14:15], v[196:197], v[150:151] op_sel_hi:[1,0,1]
	v_pk_mul_f32 v[12:13], v[162:163], v[12:13] op_sel_hi:[0,1]
	v_pk_mul_f32 v[202:203], v[162:163], v[10:11] op_sel_hi:[0,1]
	v_pk_mul_f32 v[10:11], v[162:163], v[8:9] op_sel_hi:[0,1]
	v_pk_mul_f32 v[14:15], v[162:163], v[14:15] op_sel_hi:[0,1]
	v_cvt_pk_bf16_f32 v8, v12, v13
	v_cvt_pk_bf16_f32 v9, v14, v15
	v_cvt_pk_bf16_f32 v10, v10, v11
	v_cvt_pk_bf16_f32 v11, v202, v203
	ds_write_b128 v171, v[8:11]
	ds_read_b128 v[8:11], v172
	s_waitcnt lgkmcnt(2)
	global_store_dwordx4 v[20:21], v[16:19], off nt
	s_waitcnt lgkmcnt(0)
	global_store_dwordx4 v[20:21], v[8:11], off offset:256 nt
	s_cbranch_vccnz .LBB0_488
	s_andn2_b64 vcc, exec, s[6:7]
	s_cbranch_vccnz .LBB0_487
	s_barrier
	s_branch .LBB0_487
